# G2 tile-tail rebalancing: last 256 rows (third round on 16 blocks) split into 512 16x32 pieces, per-branch K split over 4 waves + LDS reduce, gating and bf16 pack in wave 0
# speedup vs baseline: 1.0042x; 1.0042x over previous
; __device__ __forceinline__ int otid() { int t = threadIdx.x; asm volatile("" : "+v"(t)); return t; }
; __device__ __forceinline__ int tile_iters(int MT, int NTn) {
;   const int G = gridDim.x;
;   const int nx = (G % 8 == 0) ? 8 : 1;
;   const int nloc = G / nx;
;   const int nchunks = (MT * NTn + nloc - 1) / nloc;
;   return (nchunks + nx - 1) / nx;
; }
; __device__ __forceinline__ void phase_gemm_merge(const Params& p, char* smem) {
;   const bf16_t* BR = (const bf16_t*)(p.out + O_YP);
;   const bf16_t* W = (const bf16_t*)(p.ws + OFF_WBR);
;   const bf16_t* POST = (const bf16_t*)(p.ws + OFF_POST);
;   bf16_t* MG = (bf16_t*)(p.ws + OFF_MERGED);
;   const int tid_ = otid(); const int lane = tid_ & 63, wave = tid_ >> 6, wm = wave >> 1, wn = wave & 1;
;   const int MT = NT / 128, NTn = 8;
;   const int iters = tile_iters(MT, NTn);
;   for (int it = 0; it < iters; ++it) {
;     int mt, nt;
;     if (!tile_at(it, MT, NTn, mt, nt)) break;
.LBB0_11:
	s_cmp_lg_u32 s18, 28
	s_mov_b64 s[12:13], -1
	v_writelane_b32 v241, s18, 21
	s_cbranch_scc0 .LBB0_832
	v_readlane_b32 s0, v241, 21
	s_mul_hi_i32 s12, s0, 0x92492493
	s_add_i32 s12, s12, s0
	s_lshr_b32 s13, s12, 31
	s_ashr_i32 s12, s12, 2
	s_add_i32 s14, s12, s13
	s_mov_b32 s12, s14
	v_writelane_b32 v241, s12, 22
	s_nop 1
	v_writelane_b32 v241, s13, 23
	s_mul_i32 s12, s14, -7
	s_add_i32 s0, s12, s0
	v_writelane_b32 v241, s0, 24
	s_cmp_lt_i32 s0, 2
	s_mov_b64 s[0:1], 0
	s_mov_b64 s[12:13], -1
	v_writelane_b32 v241, s0, 25
	s_nop 1
	v_writelane_b32 v241, s1, 26
	s_cbranch_scc1 .LBB0_704
	v_readlane_b32 s0, v241, 24
	s_cmp_gt_i32 s0, 3
	s_cbranch_scc0 .LBB0_23
	s_cmp_gt_i32 s0, 4
	s_cbranch_scc0 .LBB0_24
	s_cmp_eq_u32 s0, 5
	s_mov_b64 s[0:1], -1
	s_cbranch_scc0 .LBB0_26
	v_readlane_b32 s12, v244, 9
	v_mov_b32_e32 v0, v178
	v_readlane_b32 s13, v244, 10
	s_load_dword s16, s[12:13], 0x0
	s_waitcnt lgkmcnt(0)
	s_and_b32 s12, s16, 7
	s_cmp_eq_u32 s12, 0
	s_cselect_b64 s[12:13], -1, 0
	s_and_b64 s[14:15], s[12:13], exec
	s_cselect_b32 s15, 8, 1
	v_cvt_f32_ubyte0_e32 v1, s15
	v_rcp_iflag_f32_e32 v1, v1
	s_sub_i32 s17, 0, s15
	s_ashr_i32 s14, s16, 31
	s_abs_i32 s16, s16
	v_mul_f32_e32 v1, 0x4f7ffffe, v1
	v_cvt_u32_f32_e32 v1, v1
	s_nop 0
	v_readfirstlane_b32 s18, v1
	s_mul_i32 s17, s17, s18
	s_mul_hi_u32 s17, s18, s17
	s_add_i32 s17, s18, s17
	s_mul_hi_u32 s18, s16, s17
	s_mul_i32 s22, s18, s15
	s_sub_i32 s16, s16, s22
	s_add_i32 s23, s18, 1
	s_sub_i32 s22, s16, s15
	s_cmp_ge_u32 s16, s15
	s_cselect_b32 s18, s23, s18
	s_cselect_b32 s16, s22, s16
	s_add_i32 s22, s18, 1
	s_cmp_ge_u32 s16, s15
	s_cselect_b32 s16, s22, s18
	s_xor_b32 s16, s16, s14
	s_sub_i32 s18, s16, s14
	s_abs_i32 s14, s18
	v_cvt_f32_u32_e32 v1, s14
	s_add_i32 s16, s18, 0x3ff
	s_sub_i32 s22, 0xfffffc01, s18
	s_xor_b32 s23, s16, s18
	v_rcp_iflag_f32_e32 v1, v1
	s_max_i32 s16, s16, s22
	s_sub_i32 s22, 0, s14
	s_ashr_i32 s23, s23, 31
	v_mul_f32_e32 v1, 0x4f7ffffe, v1
	v_cvt_u32_f32_e32 v1, v1
	s_nop 0
	v_readfirstlane_b32 s24, v1
	s_mul_i32 s22, s22, s24
	s_mul_hi_u32 s22, s24, s22
	s_add_i32 s24, s24, s22
	s_mul_hi_u32 s22, s16, s24
	s_mul_i32 s24, s22, s14
	s_sub_i32 s16, s16, s24
	s_add_i32 s25, s22, 1
	s_sub_i32 s24, s16, s14
	s_cmp_ge_u32 s16, s14
	s_cselect_b32 s22, s25, s22
	s_cselect_b32 s16, s24, s16
	s_add_i32 s24, s22, 1
	s_cmp_ge_u32 s16, s14
	s_cselect_b32 s16, s24, s22
	s_xor_b32 s16, s16, s23
	s_add_i32 s14, s15, -1
	s_sub_i32 s16, s16, s23
	s_add_i32 s16, s14, s16
	s_ashr_i32 s22, s16, 31
	s_abs_i32 s16, s16
	s_mul_hi_u32 s17, s16, s17
	s_mul_i32 s23, s17, s15
	s_sub_i32 s16, s16, s23
	s_add_i32 s24, s17, 1
	s_sub_i32 s23, s16, s15
	s_cmp_ge_u32 s16, s15
	s_cselect_b32 s17, s24, s17
	s_cselect_b32 s16, s23, s16
	s_add_i32 s23, s17, 1
	s_cmp_ge_u32 s16, s15
	s_cselect_b32 s15, s23, s17
	s_xor_b32 s15, s15, s22
	s_sub_i32 s22, s15, s22
	s_cmp_lt_i32 s22, 1
	s_cbranch_scc1 .LBB0_25
	v_readlane_b32 s15, v244, 0
	s_and_b32 s23, s14, s15
	s_and_b64 s[12:13], s[12:13], exec
	v_ashrrev_i32_e32 v2, 1, v0
	v_and_b32_e32 v4, 15, v0
	s_movk_i32 s0, 0xffc0
	v_and_b32_e32 v1, 64, v0
	s_cselect_b32 s25, 3, 0
	v_and_or_b32 v2, v2, s0, v4
	v_lshrrev_b32_e32 v0, 2, v0
	s_mov_b32 s24, 0
	s_lshr_b32 s26, s15, s25
	v_and_or_b32 v122, v0, 12, v1
	v_or_b32_e32 v123, 48, v2
	v_or_b32_e32 v124, 32, v2
	v_or_b32_e32 v125, 16, v2
	s_branch .LBB0_19

; __device__ __forceinline__ bool tile_at(int it, int MT, int NTn, int& mt, int& nt) {
;   const int G = gridDim.x;
;   const int nx = (G % 8 == 0) ? 8 : 1;
;   const int x = blockIdx.x % nx, j = blockIdx.x / nx, nloc = G / nx;
;   const int ch = x + nx * it;
;   const int q = ch * nloc + j;
;   if (q >= MT * NTn) return false;
;   const int gs = 8 * NTn;
;   const int g = q / gs, rem = q - g * gs;
;   const int gsz = min(8, MT - g * 8);
;   nt = rem / gsz;
;   mt = g * 8 + (rem - nt * gsz);
;   return true;
; }
; __device__ __forceinline__ void phase_gemm_merge(const Params& p, char* smem) {
;     ...
;     f32x4 outv[4][4];
; #pragma unroll
;     for (int i = 0; i < 4; ++i)
; #pragma unroll
;       for (int j = 0; j < 4; ++j) outv[i][j] = (f32x4){0.f, 0.f, 0.f, 0.f};
;     for (int b = 0; b < 3; ++b) {
;       f32x4 acc[4][4];
; #pragma unroll
;       for (int i = 0; i < 4; ++i)
; #pragma unroll
;         for (int j = 0; j < 4; ++j) acc[i][j] = (f32x4){0.f, 0.f, 0.f, 0.f};
.LBB0_19:
	s_lshl_b32 s12, s24, s25
	s_add_i32 s12, s12, s23
	s_mul_i32 s14, s12, s18
	s_add_i32 s14, s14, s26
	s_cmpk_gt_i32 s14, 0x3ff
	s_mov_b64 s[12:13], -1
	s_cbranch_scc1 .LBB0_18
	s_ashr_i32 s12, s14, 31
	s_lshr_b32 s12, s12, 26
	s_add_i32 s12, s14, s12
	s_ashr_i32 s15, s12, 6
	s_lshl_b32 s13, s15, 3
	s_sub_i32 s16, 0x82, s13
	s_min_u32 s16, s16, 8
	v_cvt_f32_ubyte0_e32 v0, s16
	v_rcp_iflag_f32_e32 v0, v0
	s_sub_i32 s28, 0, s16
	s_andn2_b32 s12, s12, 63
	s_sub_i32 s12, s14, s12
	v_mul_f32_e32 v0, 0x4f7ffffe, v0
	v_cvt_u32_f32_e32 v0, v0
	s_abs_i32 s27, s12
	s_ashr_i32 s17, s12, 31
	s_mul_i32 s15, s15, 56
	v_readfirstlane_b32 s29, v0
	s_mul_i32 s28, s28, s29
	s_mul_hi_u32 s28, s29, s28
	s_add_i32 s29, s29, s28
	s_mul_hi_u32 s28, s27, s29
	s_mul_i32 s29, s28, s16
	s_sub_i32 s27, s27, s29
	s_add_i32 s30, s28, 1
	s_sub_i32 s29, s27, s16
	s_cmp_ge_u32 s27, s16
	s_cselect_b32 s28, s30, s28
	s_cselect_b32 s27, s29, s27
	s_add_i32 s29, s28, 1
	s_cmp_ge_u32 s27, s16
	s_cselect_b32 s27, s29, s28
	s_xor_b32 s28, s27, s17
	s_sub_i32 s29, s28, s17
	s_mul_i32 s16, s29, s16
	s_sub_i32 s14, s14, s16
	s_add_i32 s12, s12, s13
	s_sub_i32 s14, s14, s15
	s_sub_i32 s27, s12, s16
	s_lshl_b32 s16, s14, 7
	v_lshl_or_b32 v0, s28, 7, v122
	s_lshl_b32 s14, s17, 7
	v_subrev_u32_e32 v0, s14, v0
	v_ashrrev_i32_e32 v1, 31, v0
	v_add_u32_e32 v4, s16, v123
	v_lshlrev_b64 v[0:1], 1, v[0:1]
	s_movk_i32 s0, 0x2400
	v_mad_i64_i32 v[102:103], s[14:15], v4, s0, v[0:1]
	v_add_u32_e32 v4, s16, v124
	v_mad_i64_i32 v[104:105], s[14:15], v4, s0, v[0:1]
	v_add_u32_e32 v4, s16, v125
	s_lshl_b32 s12, s29, 7
	v_mad_i64_i32 v[106:107], s[14:15], v4, s0, v[0:1]
	v_add_u32_e32 v4, s16, v2
	s_ashr_i32 s13, s12, 31
	v_mad_i64_i32 v[110:111], s[14:15], v4, s0, v[0:1]
	s_mul_i32 s31, s27, 0x60000
	s_lshl_b64 s[14:15], s[12:13], 10
	s_mul_hi_i32 s30, s27, 0x60000
	s_add_u32 s13, s8, s31
	v_mov_b32_e32 v0, 0
	s_mov_b32 s1, 0x18000
	s_addc_u32 s28, s9, s30
	s_mov_b64 s[16:17], 0
	v_mov_b32_e32 v1, v0
	s_waitcnt vmcnt(4)
	v_mov_b32_e32 v52, v0
	v_mov_b32_e32 v53, v0
	v_mov_b32_e32 v56, v0
	v_mov_b32_e32 v57, v0
	v_mov_b32_e32 v54, v0
	v_mov_b32_e32 v55, v0
	v_mov_b32_e32 v60, v0
	v_mov_b32_e32 v61, v0
	v_mov_b32_e32 v58, v0
	v_mov_b32_e32 v59, v0
	v_mov_b32_e32 v64, v0
	v_mov_b32_e32 v65, v0
	v_mov_b32_e32 v62, v0
	v_mov_b32_e32 v63, v0
	v_mov_b32_e32 v68, v0
	v_mov_b32_e32 v69, v0
	v_mov_b32_e32 v66, v0
	v_mov_b32_e32 v67, v0
	v_mov_b32_e32 v72, v0
	v_mov_b32_e32 v73, v0
	v_mov_b32_e32 v70, v0
	v_mov_b32_e32 v71, v0
	v_mov_b32_e32 v76, v0
	v_mov_b32_e32 v77, v0
	v_mov_b32_e32 v74, v0
	v_mov_b32_e32 v75, v0
	v_mov_b32_e32 v80, v0
	v_mov_b32_e32 v81, v0
	v_mov_b32_e32 v78, v0
	v_mov_b32_e32 v79, v0
	v_mov_b32_e32 v84, v0
	v_mov_b32_e32 v85, v0
	v_mov_b32_e32 v82, v0
	v_mov_b32_e32 v83, v0
	v_mov_b32_e32 v88, v0
	v_mov_b32_e32 v89, v0
	v_mov_b32_e32 v86, v0
	v_mov_b32_e32 v87, v0
	v_mov_b32_e32 v92, v0
	v_mov_b32_e32 v93, v0
	v_mov_b32_e32 v90, v0
	v_mov_b32_e32 v91, v0
	v_mov_b32_e32 v96, v0
	v_mov_b32_e32 v97, v0
	v_mov_b32_e32 v94, v0
	v_mov_b32_e32 v95, v0
	v_mov_b32_e32 v100, v0
	v_mov_b32_e32 v101, v0
	v_mov_b32_e32 v98, v0
	v_mov_b32_e32 v99, v0
	v_mov_b32_e32 v112, v0
	v_mov_b32_e32 v113, v0
	v_mov_b32_e32 v108, v0
	v_mov_b32_e32 v109, v0
	v_mov_b32_e32 v116, v0
	v_mov_b32_e32 v117, v0
	v_mov_b32_e32 v114, v0
	v_mov_b32_e32 v115, v0
	v_mov_b32_e32 v120, v0
	v_mov_b32_e32 v121, v0
	v_mov_b32_e32 v118, v0
	v_mov_b32_e32 v119, v0
	s_mov_b32 s0, 0x30000
	s_mov_b64 s[38:39], 0x800

; __device__ __forceinline__ float bflo(unsigned u) { return __uint_as_float(u << 16); }
; __device__ __forceinline__ float bfhi(unsigned u) { return __uint_as_float(u & 0xffff0000u); }
; __device__ __forceinline__ float sigmoidf_(float x) { return frcp_(1.f + __expf(-x)); }
; __device__ __forceinline__ void mma_ktile(const bf16_t* cA, const bf16_t* cB, int fo0, int fo1, f32x4 (&acc)[4][4]) {
; #pragma unroll
;   for (int ks = 0; ks < 2; ++ks) {
;     const int fo = ks ? fo1 : fo0;
;     bf16x8 af[4], bfr[4];
; #pragma unroll
;     for (int i = 0; i < 4; ++i) af[i] = *(const bf16x8*)(cA + i * 16 * LDS_STRIDE + fo);
; #pragma unroll
;     for (int j = 0; j < 4; ++j) bfr[j] = *(const bf16x8*)(cB + j * 16 * LDS_STRIDE + fo);
; #pragma unroll
;     for (int i = 0; i < 4; ++i)
; #pragma unroll
;       for (int j = 0; j < 4; ++j)
;         acc[i][j] = __builtin_amdgcn_mfma_f32_16x16x32_bf16(bfr[j], af[i], acc[i][j], 0, 0, 0);
;   }
; }
; __device__ __forceinline__ void phase_gemm_merge(const Params& p, char* smem) {
;     ...
;     for (int b = 0; b < 3; ++b) {
;       f32x4 acc[4][4];
; #pragma unroll
;       for (int i = 0; i < 4; ++i)
; #pragma unroll
;         for (int j = 0; j < 4; ++j) acc[i][j] = (f32x4){0.f, 0.f, 0.f, 0.f};
;       gemm_core<false>(BR + (size_t)mt * 128 * 1536 + b * 512, 1536, W + ((size_t)b * 1024 + nt * 128) * 512, 512, 512, acc, smem);
; #pragma unroll
;       for (int i = 0; i < 4; ++i) {
;         const int m = mt * 128 + wm * 64 + i * 16 + (lane & 15);
; #pragma unroll
;         for (int j = 0; j < 4; ++j) {
;           const int n = nt * 128 + wn * 64 + j * 16 + (lane >> 4) * 4;
;           const uint2 gz = *(const uint2*)(POST + (size_t)m * POST_W + QC_GATE + b * 1024 + n);
;           outv[i][j][0] += sigmoidf_(bflo(gz.x)) * acc[i][j][0];
;           outv[i][j][1] += sigmoidf_(bfhi(gz.x)) * acc[i][j][1];
;           outv[i][j][2] += sigmoidf_(bflo(gz.y)) * acc[i][j][2];
;           outv[i][j][3] += sigmoidf_(bfhi(gz.y)) * acc[i][j][3];
;         }
;       }
.LBB0_25:
	v_readlane_b32 s12, v244, 9
	v_readlane_b32 s13, v244, 10
	v_readlane_b32 s14, v244, 0
	v_readlane_b32 s0, v244, 7
	v_readlane_b32 s1, v244, 8
	s_load_dword s16, s[12:13], 0x0
	v_and_b32_e32 v0, 15, v178
	v_bfe_u32 v1, v178, 4, 2
	v_lshrrev_b32_e32 v2, 6, v178
	v_mul_u32_u24_e32 v4, 0xc00, v0
	v_lshlrev_b32_e32 v5, 10, v0
	v_readfirstlane_b32 s15, v2
	v_lshl_add_u32 v4, v2, 8, v4
	v_lshl_add_u32 v5, v2, 8, v5
	v_lshl_add_u32 v4, v1, 4, v4
	v_lshl_add_u32 v5, v1, 4, v5
	v_add_u32_e32 v6, 0x4000, v5
	v_mul_u32_u24_e32 v176, 0x2400, v0
	v_lshl_add_u32 v176, v1, 3, v176
	v_lshlrev_b32_e32 v177, 11, v0
	v_lshl_add_u32 v177, v1, 3, v177
	v_and_b32_e32 v7, 63, v178
	v_lshlrev_b32_e32 v7, 4, v7
	s_waitcnt lgkmcnt(0)
.Lg2t_loop:
	s_cmpk_gt_i32 s14, 0x1ff
	s_cbranch_scc1 .Lg2t_done
	s_and_b32 s17, s14, 31
	s_lshr_b32 s18, s14, 5
	s_mul_i32 s22, s18, 0xc000
	s_add_u32 s22, s22, 0x3000000
	s_add_u32 s24, s8, s22
	s_addc_u32 s25, s9, 0
	s_lshl_b32 s22, s17, 15
	s_add_u32 s22, s22, 0x237f8000
	s_add_u32 s26, s10, s22
	s_addc_u32 s27, s11, 0
	s_add_u32 s28, s26, 0x100000
	s_addc_u32 s29, s27, 0
	s_add_u32 s12, s28, 0x100000
	s_addc_u32 s13, s29, 0
	s_mul_i32 s22, s18, 0x24000
	s_lshl_b32 s23, s17, 6
	s_add_u32 s22, s22, s23
	s_add_u32 s22, s22, 0x15b21400
	s_add_u32 s22, s10, s22
	s_addc_u32 s23, s11, 0
	global_load_dwordx2 v[188:189], v176, s[22:23] offset:-2048
	global_load_dwordx2 v[190:191], v176, s[22:23] offset:-2016
	global_load_dwordx2 v[192:193], v176, s[22:23]
	global_load_dwordx2 v[194:195], v176, s[22:23] offset:32
	global_load_dwordx2 v[196:197], v176, s[22:23] offset:2048
	global_load_dwordx2 v[198:199], v176, s[22:23] offset:2080
	global_load_dwordx4 v[8:11], v4, s[24:25]
	global_load_dwordx4 v[56:59], v5, s[26:27]
	global_load_dwordx4 v[72:75], v6, s[26:27]
	global_load_dwordx4 v[12:15], v4, s[24:25] offset:64
	global_load_dwordx4 v[60:63], v5, s[26:27] offset:64
	global_load_dwordx4 v[76:79], v6, s[26:27] offset:64
	global_load_dwordx4 v[16:19], v4, s[24:25] offset:128
	global_load_dwordx4 v[64:67], v5, s[26:27] offset:128
	global_load_dwordx4 v[80:83], v6, s[26:27] offset:128
	global_load_dwordx4 v[20:23], v4, s[24:25] offset:192
	global_load_dwordx4 v[68:71], v5, s[26:27] offset:192
	global_load_dwordx4 v[84:87], v6, s[26:27] offset:192
	global_load_dwordx4 v[24:27], v4, s[24:25] offset:1024
	global_load_dwordx4 v[88:91], v5, s[28:29]
	global_load_dwordx4 v[104:107], v6, s[28:29]
	global_load_dwordx4 v[28:31], v4, s[24:25] offset:1088
	global_load_dwordx4 v[92:95], v5, s[28:29] offset:64
	global_load_dwordx4 v[108:111], v6, s[28:29] offset:64
	global_load_dwordx4 v[32:35], v4, s[24:25] offset:1152
	global_load_dwordx4 v[96:99], v5, s[28:29] offset:128
	global_load_dwordx4 v[112:115], v6, s[28:29] offset:128
	global_load_dwordx4 v[36:39], v4, s[24:25] offset:1216
	global_load_dwordx4 v[100:103], v5, s[28:29] offset:192
	global_load_dwordx4 v[116:119], v6, s[28:29] offset:192
	global_load_dwordx4 v[40:43], v4, s[24:25] offset:2048
	global_load_dwordx4 v[120:123], v5, s[12:13]
	global_load_dwordx4 v[136:139], v6, s[12:13]
	global_load_dwordx4 v[44:47], v4, s[24:25] offset:2112
	global_load_dwordx4 v[124:127], v5, s[12:13] offset:64
	global_load_dwordx4 v[140:143], v6, s[12:13] offset:64
	global_load_dwordx4 v[48:51], v4, s[24:25] offset:2176
	global_load_dwordx4 v[128:131], v5, s[12:13] offset:128
	global_load_dwordx4 v[144:147], v6, s[12:13] offset:128
	global_load_dwordx4 v[52:55], v4, s[24:25] offset:2240
	global_load_dwordx4 v[132:135], v5, s[12:13] offset:192
	global_load_dwordx4 v[148:151], v6, s[12:13] offset:192
	s_barrier
	s_waitcnt vmcnt(33)
	v_mfma_f32_16x16x32_bf16 v[152:155], v[56:59], v[8:11], 0
	v_mfma_f32_16x16x32_bf16 v[156:159], v[72:75], v[8:11], 0
	s_waitcnt vmcnt(30)
	v_mfma_f32_16x16x32_bf16 v[152:155], v[60:63], v[12:15], v[152:155]
	v_mfma_f32_16x16x32_bf16 v[156:159], v[76:79], v[12:15], v[156:159]
	s_waitcnt vmcnt(27)
	v_mfma_f32_16x16x32_bf16 v[152:155], v[64:67], v[16:19], v[152:155]
	v_mfma_f32_16x16x32_bf16 v[156:159], v[80:83], v[16:19], v[156:159]
	s_waitcnt vmcnt(24)
	v_mfma_f32_16x16x32_bf16 v[152:155], v[68:71], v[20:23], v[152:155]
	v_mfma_f32_16x16x32_bf16 v[156:159], v[84:87], v[20:23], v[156:159]
	s_waitcnt vmcnt(21)
	v_mfma_f32_16x16x32_bf16 v[160:163], v[88:91], v[24:27], 0
	v_mfma_f32_16x16x32_bf16 v[164:167], v[104:107], v[24:27], 0
	s_waitcnt vmcnt(18)
	v_mfma_f32_16x16x32_bf16 v[160:163], v[92:95], v[28:31], v[160:163]
	v_mfma_f32_16x16x32_bf16 v[164:167], v[108:111], v[28:31], v[164:167]
	s_waitcnt vmcnt(15)
	v_mfma_f32_16x16x32_bf16 v[160:163], v[96:99], v[32:35], v[160:163]
	v_mfma_f32_16x16x32_bf16 v[164:167], v[112:115], v[32:35], v[164:167]
	s_waitcnt vmcnt(12)
	v_mfma_f32_16x16x32_bf16 v[160:163], v[100:103], v[36:39], v[160:163]
	v_mfma_f32_16x16x32_bf16 v[164:167], v[116:119], v[36:39], v[164:167]
	s_waitcnt vmcnt(9)
	v_mfma_f32_16x16x32_bf16 v[168:171], v[120:123], v[40:43], 0
	v_mfma_f32_16x16x32_bf16 v[172:175], v[136:139], v[40:43], 0
	s_waitcnt vmcnt(6)
	v_mfma_f32_16x16x32_bf16 v[168:171], v[124:127], v[44:47], v[168:171]
	v_mfma_f32_16x16x32_bf16 v[172:175], v[140:143], v[44:47], v[172:175]
	s_waitcnt vmcnt(3)
	v_mfma_f32_16x16x32_bf16 v[168:171], v[128:131], v[48:51], v[168:171]
	v_mfma_f32_16x16x32_bf16 v[172:175], v[144:147], v[48:51], v[172:175]
	s_waitcnt vmcnt(0)
	v_mfma_f32_16x16x32_bf16 v[168:171], v[132:135], v[52:55], v[168:171]
	v_mfma_f32_16x16x32_bf16 v[172:175], v[148:151], v[52:55], v[172:175]
	s_nop 15
	s_cmp_eq_u32 s15, 0
	s_cbranch_scc1 .Lg2t_w0
	s_mul_i32 s22, s15, 0x1800
	v_add_u32_e32 v8, s22, v7
	ds_write_b128 v8, v[152:155]
	ds_write_b128 v8, v[156:159] offset:1024
	ds_write_b128 v8, v[160:163] offset:2048
	ds_write_b128 v8, v[164:167] offset:3072
	ds_write_b128 v8, v[168:171] offset:4096
	ds_write_b128 v8, v[172:175] offset:5120
	s_waitcnt lgkmcnt(0)
	s_barrier
	s_branch .Lg2t_next
; __device__ __forceinline__ float bflo(unsigned u) { return __uint_as_float(u << 16); }
; __device__ __forceinline__ float bfhi(unsigned u) { return __uint_as_float(u & 0xffff0000u); }
; __device__ __forceinline__ float sigmoidf_(float x) { return frcp_(1.f + __expf(-x)); }
; __device__ __forceinline__ void phase_gemm_merge(const Params& p, char* smem) {
;     ...
; #pragma unroll
;       for (int i = 0; i < 4; ++i) {
;         const int m = mt * 128 + wm * 64 + i * 16 + (lane & 15);
; #pragma unroll
;         for (int j = 0; j < 4; ++j) {
;           const int n = nt * 128 + wn * 64 + j * 16 + (lane >> 4) * 4;
;           const uint2 gz = *(const uint2*)(POST + (size_t)m * POST_W + QC_GATE + b * 1024 + n);
;           outv[i][j][0] += sigmoidf_(bflo(gz.x)) * acc[i][j][0];
;           outv[i][j][1] += sigmoidf_(bfhi(gz.x)) * acc[i][j][1];
;           outv[i][j][2] += sigmoidf_(bflo(gz.y)) * acc[i][j][2];
;           outv[i][j][3] += sigmoidf_(bfhi(gz.y)) * acc[i][j][3];
;         }
;       }
.Lg2t_w0:
	s_barrier
	s_lshl_b32 s22, s18, 15
	s_lshl_b32 s23, s17, 6
	s_add_u32 s22, s22, s23
	s_add_u32 s22, s22, 0x2000000
	s_add_u32 s24, s0, s22
	s_addc_u32 s25, s1, 0
	ds_read_b128 v[8:11], v7 offset:6144
	ds_read_b128 v[12:15], v7 offset:7168
	ds_read_b128 v[16:19], v7 offset:8192
	ds_read_b128 v[20:23], v7 offset:9216
	ds_read_b128 v[24:27], v7 offset:10240
	ds_read_b128 v[28:31], v7 offset:11264
	ds_read_b128 v[32:35], v7 offset:12288
	ds_read_b128 v[36:39], v7 offset:13312
	ds_read_b128 v[40:43], v7 offset:14336
	ds_read_b128 v[44:47], v7 offset:15360
	ds_read_b128 v[48:51], v7 offset:16384
	ds_read_b128 v[52:55], v7 offset:17408
	ds_read_b128 v[56:59], v7 offset:18432
	ds_read_b128 v[60:63], v7 offset:19456
	ds_read_b128 v[64:67], v7 offset:20480
	ds_read_b128 v[68:71], v7 offset:21504
	ds_read_b128 v[72:75], v7 offset:22528
	ds_read_b128 v[76:79], v7 offset:23552
	s_waitcnt lgkmcnt(0)
	v_pk_add_f32 v[152:153], v[152:153], v[8:9]
	v_pk_add_f32 v[154:155], v[154:155], v[10:11]
	v_pk_add_f32 v[156:157], v[156:157], v[12:13]
	v_pk_add_f32 v[158:159], v[158:159], v[14:15]
	v_pk_add_f32 v[160:161], v[160:161], v[16:17]
	v_pk_add_f32 v[162:163], v[162:163], v[18:19]
	v_pk_add_f32 v[164:165], v[164:165], v[20:21]
	v_pk_add_f32 v[166:167], v[166:167], v[22:23]
	v_pk_add_f32 v[168:169], v[168:169], v[24:25]
	v_pk_add_f32 v[170:171], v[170:171], v[26:27]
	v_pk_add_f32 v[172:173], v[172:173], v[28:29]
	v_pk_add_f32 v[174:175], v[174:175], v[30:31]
	v_pk_add_f32 v[152:153], v[152:153], v[32:33]
	v_pk_add_f32 v[154:155], v[154:155], v[34:35]
	v_pk_add_f32 v[156:157], v[156:157], v[36:37]
	v_pk_add_f32 v[158:159], v[158:159], v[38:39]
	v_pk_add_f32 v[160:161], v[160:161], v[40:41]
	v_pk_add_f32 v[162:163], v[162:163], v[42:43]
	v_pk_add_f32 v[164:165], v[164:165], v[44:45]
	v_pk_add_f32 v[166:167], v[166:167], v[46:47]
	v_pk_add_f32 v[168:169], v[168:169], v[48:49]
	v_pk_add_f32 v[170:171], v[170:171], v[50:51]
	v_pk_add_f32 v[172:173], v[172:173], v[52:53]
	v_pk_add_f32 v[174:175], v[174:175], v[54:55]
	v_pk_add_f32 v[152:153], v[152:153], v[56:57]
	v_pk_add_f32 v[154:155], v[154:155], v[58:59]
	v_pk_add_f32 v[156:157], v[156:157], v[60:61]
	v_pk_add_f32 v[158:159], v[158:159], v[62:63]
	v_pk_add_f32 v[160:161], v[160:161], v[64:65]
	v_pk_add_f32 v[162:163], v[162:163], v[66:67]
	v_pk_add_f32 v[164:165], v[164:165], v[68:69]
	v_pk_add_f32 v[166:167], v[166:167], v[70:71]
	v_pk_add_f32 v[168:169], v[168:169], v[72:73]
	v_pk_add_f32 v[170:171], v[170:171], v[74:75]
	v_pk_add_f32 v[172:173], v[172:173], v[76:77]
	v_pk_add_f32 v[174:175], v[174:175], v[78:79]
	s_waitcnt vmcnt(0)
; __device__ __forceinline__ unsigned pack2(float a, float b) { return (unsigned)f2bf(a) | ((unsigned)f2bf(b) << 16); }
; __device__ __forceinline__ float bflo(unsigned u) { return __uint_as_float(u << 16); }
; __device__ __forceinline__ float bfhi(unsigned u) { return __uint_as_float(u & 0xffff0000u); }
; __device__ __forceinline__ float sigmoidf_(float x) { return frcp_(1.f + __expf(-x)); }
; __device__ __forceinline__ void phase_gemm_merge(const Params& p, char* smem) {
;     ...
; #pragma unroll
;       for (int i = 0; i < 4; ++i) {
;         const int m = mt * 128 + wm * 64 + i * 16 + (lane & 15);
; #pragma unroll
;         for (int j = 0; j < 4; ++j) {
;           const int n = nt * 128 + wn * 64 + j * 16 + (lane >> 4) * 4;
;           const uint2 gz = *(const uint2*)(POST + (size_t)m * POST_W + QC_GATE + b * 1024 + n);
;           outv[i][j][0] += sigmoidf_(bflo(gz.x)) * acc[i][j][0];
;           outv[i][j][1] += sigmoidf_(bfhi(gz.x)) * acc[i][j][1];
;           outv[i][j][2] += sigmoidf_(bflo(gz.y)) * acc[i][j][2];
;           outv[i][j][3] += sigmoidf_(bfhi(gz.y)) * acc[i][j][3];
;         }
;       }
;     }
; #pragma unroll
;     for (int i = 0; i < 4; ++i) {
;       const int m = mt * 128 + wm * 64 + i * 16 + (lane & 15);
; #pragma unroll
;       for (int j = 0; j < 4; ++j) {
;         const int n = nt * 128 + wn * 64 + j * 16 + (lane >> 4) * 4;
;         uint2 o;
;         o.x = pack2(outv[i][j][0], outv[i][j][1]);
;         o.y = pack2(outv[i][j][2], outv[i][j][3]);
;         *(uint2*)(MG + (size_t)m * 1024 + n) = o;
;       }
	v_lshlrev_b32_e32 v100, 16, v188
	v_and_b32_e32 v101, 0xffff0000, v188
	v_lshlrev_b32_e32 v102, 16, v189
	v_and_b32_e32 v103, 0xffff0000, v189
	v_mul_f32_e32 v100, 0xbfb8aa3b, v100
	v_mul_f32_e32 v101, 0xbfb8aa3b, v101
	v_mul_f32_e32 v102, 0xbfb8aa3b, v102
	v_mul_f32_e32 v103, 0xbfb8aa3b, v103
	v_exp_f32_e32 v100, v100
	v_exp_f32_e32 v101, v101
	v_exp_f32_e32 v102, v102
	v_exp_f32_e32 v103, v103
	s_nop 0
	v_add_f32_e32 v100, 1.0, v100
	v_add_f32_e32 v101, 1.0, v101
	v_add_f32_e32 v102, 1.0, v102
	v_add_f32_e32 v103, 1.0, v103
	v_rcp_f32_e32 v100, v100
	v_rcp_f32_e32 v101, v101
	v_rcp_f32_e32 v102, v102
	v_rcp_f32_e32 v103, v103
	s_nop 0
	v_pk_mul_f32 v[92:93], v[100:101], v[152:153]
	v_pk_mul_f32 v[94:95], v[102:103], v[154:155]
	v_lshlrev_b32_e32 v100, 16, v192
	v_and_b32_e32 v101, 0xffff0000, v192
	v_lshlrev_b32_e32 v102, 16, v193
	v_and_b32_e32 v103, 0xffff0000, v193
	v_mul_f32_e32 v100, 0xbfb8aa3b, v100
	v_mul_f32_e32 v101, 0xbfb8aa3b, v101
	v_mul_f32_e32 v102, 0xbfb8aa3b, v102
	v_mul_f32_e32 v103, 0xbfb8aa3b, v103
	v_exp_f32_e32 v100, v100
	v_exp_f32_e32 v101, v101
	v_exp_f32_e32 v102, v102
	v_exp_f32_e32 v103, v103
	s_nop 0
	v_add_f32_e32 v100, 1.0, v100
	v_add_f32_e32 v101, 1.0, v101
	v_add_f32_e32 v102, 1.0, v102
	v_add_f32_e32 v103, 1.0, v103
	v_rcp_f32_e32 v100, v100
	v_rcp_f32_e32 v101, v101
	v_rcp_f32_e32 v102, v102
	v_rcp_f32_e32 v103, v103
	s_nop 0
	v_pk_fma_f32 v[92:93], v[100:101], v[160:161], v[92:93]
	v_pk_fma_f32 v[94:95], v[102:103], v[162:163], v[94:95]
	v_lshlrev_b32_e32 v100, 16, v196
	v_and_b32_e32 v101, 0xffff0000, v196
	v_lshlrev_b32_e32 v102, 16, v197
	v_and_b32_e32 v103, 0xffff0000, v197
	v_mul_f32_e32 v100, 0xbfb8aa3b, v100
	v_mul_f32_e32 v101, 0xbfb8aa3b, v101
	v_mul_f32_e32 v102, 0xbfb8aa3b, v102
	v_mul_f32_e32 v103, 0xbfb8aa3b, v103
	v_exp_f32_e32 v100, v100
	v_exp_f32_e32 v101, v101
	v_exp_f32_e32 v102, v102
	v_exp_f32_e32 v103, v103
	s_nop 0
	v_add_f32_e32 v100, 1.0, v100
	v_add_f32_e32 v101, 1.0, v101
	v_add_f32_e32 v102, 1.0, v102
	v_add_f32_e32 v103, 1.0, v103
	v_rcp_f32_e32 v100, v100
	v_rcp_f32_e32 v101, v101
	v_rcp_f32_e32 v102, v102
	v_rcp_f32_e32 v103, v103
	s_nop 0
	v_pk_fma_f32 v[92:93], v[100:101], v[168:169], v[92:93]
	v_pk_fma_f32 v[94:95], v[102:103], v[170:171], v[94:95]
	v_cvt_pk_bf16_f32 v108, v92, v93
	v_cvt_pk_bf16_f32 v109, v94, v95
	v_lshlrev_b32_e32 v100, 16, v190
	v_and_b32_e32 v101, 0xffff0000, v190
	v_lshlrev_b32_e32 v102, 16, v191
	v_and_b32_e32 v103, 0xffff0000, v191
	v_mul_f32_e32 v100, 0xbfb8aa3b, v100
	v_mul_f32_e32 v101, 0xbfb8aa3b, v101
	v_mul_f32_e32 v102, 0xbfb8aa3b, v102
	v_mul_f32_e32 v103, 0xbfb8aa3b, v103
	v_exp_f32_e32 v100, v100
	v_exp_f32_e32 v101, v101
	v_exp_f32_e32 v102, v102
	v_exp_f32_e32 v103, v103
	s_nop 0
	v_add_f32_e32 v100, 1.0, v100
	v_add_f32_e32 v101, 1.0, v101
	v_add_f32_e32 v102, 1.0, v102
	v_add_f32_e32 v103, 1.0, v103
	v_rcp_f32_e32 v100, v100
	v_rcp_f32_e32 v101, v101
	v_rcp_f32_e32 v102, v102
	v_rcp_f32_e32 v103, v103
	s_nop 0
	v_pk_mul_f32 v[96:97], v[100:101], v[156:157]
	v_pk_mul_f32 v[98:99], v[102:103], v[158:159]
	v_lshlrev_b32_e32 v100, 16, v194
	v_and_b32_e32 v101, 0xffff0000, v194
	v_lshlrev_b32_e32 v102, 16, v195
	v_and_b32_e32 v103, 0xffff0000, v195
	v_mul_f32_e32 v100, 0xbfb8aa3b, v100
	v_mul_f32_e32 v101, 0xbfb8aa3b, v101
	v_mul_f32_e32 v102, 0xbfb8aa3b, v102
	v_mul_f32_e32 v103, 0xbfb8aa3b, v103
	v_exp_f32_e32 v100, v100
	v_exp_f32_e32 v101, v101
	v_exp_f32_e32 v102, v102
	v_exp_f32_e32 v103, v103
	s_nop 0
	v_add_f32_e32 v100, 1.0, v100
	v_add_f32_e32 v101, 1.0, v101
	v_add_f32_e32 v102, 1.0, v102
	v_add_f32_e32 v103, 1.0, v103
	v_rcp_f32_e32 v100, v100
	v_rcp_f32_e32 v101, v101
	v_rcp_f32_e32 v102, v102
	v_rcp_f32_e32 v103, v103
	s_nop 0
	v_pk_fma_f32 v[96:97], v[100:101], v[164:165], v[96:97]
	v_pk_fma_f32 v[98:99], v[102:103], v[166:167], v[98:99]
	v_lshlrev_b32_e32 v100, 16, v198
	v_and_b32_e32 v101, 0xffff0000, v198
	v_lshlrev_b32_e32 v102, 16, v199
	v_and_b32_e32 v103, 0xffff0000, v199
	v_mul_f32_e32 v100, 0xbfb8aa3b, v100
	v_mul_f32_e32 v101, 0xbfb8aa3b, v101
	v_mul_f32_e32 v102, 0xbfb8aa3b, v102
	v_mul_f32_e32 v103, 0xbfb8aa3b, v103
	v_exp_f32_e32 v100, v100
	v_exp_f32_e32 v101, v101
	v_exp_f32_e32 v102, v102
	v_exp_f32_e32 v103, v103
	s_nop 0
	v_add_f32_e32 v100, 1.0, v100
	v_add_f32_e32 v101, 1.0, v101
	v_add_f32_e32 v102, 1.0, v102
	v_add_f32_e32 v103, 1.0, v103
	v_rcp_f32_e32 v100, v100
	v_rcp_f32_e32 v101, v101
	v_rcp_f32_e32 v102, v102
	v_rcp_f32_e32 v103, v103
	s_nop 0
	v_pk_fma_f32 v[96:97], v[100:101], v[172:173], v[96:97]
	v_pk_fma_f32 v[98:99], v[102:103], v[174:175], v[98:99]
	v_cvt_pk_bf16_f32 v110, v96, v97
	v_cvt_pk_bf16_f32 v111, v98, v99
	global_store_dwordx2 v177, v[108:109], s[24:25]
	global_store_dwordx2 v177, v[110:111], s[24:25] offset:32
.Lg2t_next:
	s_add_i32 s14, s14, s16
	s_branch .Lg2t_loop
.Lg2t_done:
	s_mov_b64 s[0:1], 0
